# attention cmp branch: folded 125 more canonicalising v_max_f32 x,x into their consuming max
# speedup vs baseline: 1.0043x; 1.0043x over previous
.LBB0_1076:
	s_nop 10
	v_max_f32_e32 v39, v18, v2
	v_max_f32_e32 v41, v19, v3
	v_max3_f32 v39, v39, s75, v41
	v_max_f32_e32 v41, v20, v4
	v_max_f32_e32 v43, v21, v5
	v_max3_f32 v39, v39, v41, v43
	v_max_f32_e32 v41, v22, v6
	v_max_f32_e32 v43, v23, v7
	v_max3_f32 v39, v39, v41, v43
	v_max_f32_e32 v41, v24, v8
	v_max_f32_e32 v43, v25, v9
	v_max3_f32 v39, v39, v41, v43
	v_max_f32_e32 v41, v26, v10
	v_max_f32_e32 v43, v27, v11
	v_max3_f32 v39, v39, v41, v43
	v_max_f32_e32 v41, v28, v12
	v_max_f32_e32 v43, v29, v13
	v_max3_f32 v39, v39, v41, v43
	v_max_f32_e32 v41, v30, v14
	v_max_f32_e32 v43, v31, v15
	v_max3_f32 v39, v39, v41, v43
	v_max_f32_e32 v41, v32, v16
	v_max_f32_e32 v44, v33, v33
	v_max_f32_e32 v43, v44, v17
	v_max3_f32 v41, v39, v41, v43
	s_branch .LBB0_1078

.LBB0_1081:
	s_nop 10
	v_max_f32_e32 v34, v146, v130
	v_max_f32_e32 v35, v147, v131
	v_max3_f32 v34, v41, v34, v35
	v_max_f32_e32 v35, v148, v132
	v_max_f32_e32 v41, v149, v133
	v_max3_f32 v34, v34, v35, v41
	v_max_f32_e32 v35, v150, v134
	v_max_f32_e32 v41, v151, v135
	v_max3_f32 v34, v34, v35, v41
	v_max_f32_e32 v35, v152, v136
	v_max_f32_e32 v41, v153, v137
	v_max3_f32 v34, v34, v35, v41
	v_max_f32_e32 v35, v154, v138
	v_max_f32_e32 v41, v155, v139
	v_max3_f32 v34, v34, v35, v41
	v_max_f32_e32 v35, v156, v140
	v_max_f32_e32 v41, v157, v141
	v_max3_f32 v34, v34, v35, v41
	v_max_f32_e32 v35, v158, v142
	v_max_f32_e32 v41, v159, v143
	v_max3_f32 v34, v34, v35, v41
	v_max_f32_e32 v35, v160, v144
	v_max_f32_e32 v42, v161, v161
	v_max_f32_e32 v41, v42, v145
	v_max3_f32 v41, v34, v35, v41
	s_cmp_gt_i32 s72, 1
	s_cselect_b64 s[10:11], -1, 0
	s_cmp_lt_i32 s72, 2
	s_cbranch_scc1 .LBB0_1087

.LBB0_1084:
	s_nop 10
	v_max_f32_e32 v34, v114, v98
	v_max_f32_e32 v35, v115, v99
	v_max3_f32 v34, v41, v34, v35
	v_max_f32_e32 v35, v116, v100
	v_max_f32_e32 v41, v117, v101
	v_max3_f32 v34, v34, v35, v41
	v_max_f32_e32 v35, v118, v102
	v_max_f32_e32 v41, v119, v103
	v_max3_f32 v34, v34, v35, v41
	v_max_f32_e32 v35, v120, v104
	v_max_f32_e32 v41, v121, v105
	v_max3_f32 v34, v34, v35, v41
	v_max_f32_e32 v35, v122, v106
	v_max_f32_e32 v41, v123, v107
	v_max3_f32 v34, v34, v35, v41
	v_max_f32_e32 v35, v124, v108
	v_max_f32_e32 v41, v125, v109
	v_max3_f32 v34, v34, v35, v41
	v_max_f32_e32 v35, v126, v110
	v_max_f32_e32 v41, v127, v111
	v_max3_f32 v34, v34, v35, v41
	v_max_f32_e32 v35, v128, v112
	v_max_f32_e32 v42, v129, v129
	v_max_f32_e32 v41, v42, v113
	v_max3_f32 v41, v34, v35, v41
	s_cmp_gt_i32 s72, 2
	s_cselect_b64 s[94:95], -1, 0
	s_cmp_lt_i32 s72, 3
	s_cbranch_scc0 .LBB0_1088

.LBB0_1090:
	s_nop 10
	v_max_f32_e32 v34, v82, v66
	v_max_f32_e32 v35, v83, v67
	v_max3_f32 v34, v41, v34, v35
	v_max_f32_e32 v35, v84, v68
	v_max_f32_e32 v40, v85, v69
	v_max3_f32 v34, v34, v35, v40
	v_max_f32_e32 v35, v86, v70
	v_max_f32_e32 v40, v87, v71
	v_max3_f32 v34, v34, v35, v40
	v_max_f32_e32 v35, v88, v72
	v_max_f32_e32 v40, v89, v73
	v_max3_f32 v34, v34, v35, v40
	v_max_f32_e32 v35, v90, v74
	v_max_f32_e32 v40, v91, v75
	v_max3_f32 v34, v34, v35, v40
	v_max_f32_e32 v35, v92, v76
	v_max_f32_e32 v40, v93, v77
	v_max3_f32 v34, v34, v35, v40
	v_max_f32_e32 v35, v94, v78
	v_max_f32_e32 v40, v95, v79
	v_max3_f32 v34, v34, v35, v40
	v_max_f32_e32 v35, v96, v80
	v_max_f32_e32 v40, v97, v81
	v_max3_f32 v41, v34, v35, v40
